# cleanup: removed the unreachable per-row memory-norm loop from A7 (same code paths as v69)
# baseline (speedup 1.0000x reference)
; #define LAS __attribute__((address_space(3)))
; DI unsigned xb_xcc_id() { return (unsigned)__builtin_amdgcn_s_getreg((3 << 11) | 20) & 0xFu; }
; DI void xcd_barrier(unsigned* bar, volatile LAS unsigned* st, bool leader, unsigned G) {
;     asm volatile("s_waitcnt vmcnt(0)" ::: "memory");
;     __syncthreads();
;     if (leader) {
;         const unsigned x = xb_xcc_id();
;         __builtin_amdgcn_s_waitcnt(0);
;         unsigned nloc = st[0], nx = st[1];
;         if (nloc == 0u) { xcd_barrier_complete(bar, x, G, nloc, nx); st[0] = nloc; st[1] = nx; }
; __global__ void __launch_bounds__(512, 2) mega(Args args) {
;     ...
;                 if (half == 0) for (int m = gw; m < 3072; m += NGW) { const float* mi = m < 1024 ? in.mem_prompt + (size_t)m * D : in.mem_sample + (size_t)(m - 1024) * D;
;                     norm_row<false, true>(mi, nullptr, nullptr, nullptr, in.g_mem + l * D, MNb + (size_t)m * D, lane); }
.LBB0_989:
	s_cmpk_gt_i32 s2, 0xbff
	v_readlane_b32 s16, v255, 21
	s_waitcnt lgkmcnt(0)
	s_cselect_b64 s[10:11], -1, 0
	v_readlane_b32 s17, v255, 22
	s_or_b64 s[10:11], s[16:17], s[10:11]
	s_and_b64 vcc, exec, s[10:11]
.LBB0_994:
	v_readlane_b32 s6, v255, 18
	s_add_i32 s6, s6, 7
	v_readlane_b32 s4, v255, 1
	v_readlane_b32 s5, v255, 2
	s_cmp_gt_i32 s6, s4
	s_cselect_b64 s[2:3], -1, 0
	s_cmp_lt_i32 s6, s5
	s_cselect_b64 s[4:5], -1, 0
	s_and_b64 s[2:3], s[2:3], s[4:5]
	v_writelane_b32 v255, s6, 18
	s_andn2_b64 vcc, exec, s[2:3]
	s_or_b64 vcc, vcc, s[90:91]
	s_cbranch_vccnz .LBB0_112
	s_mov_b64 s[4:5], s[62:63]
	v_mov_b32_e32 v0, v213
	s_waitcnt vmcnt(0)
	s_waitcnt vmcnt(0)
	v_cmp_eq_u32_e32 vcc, 0, v0
	s_barrier
	s_and_saveexec_b64 s[2:3], vcc
	s_cbranch_execz .LBB0_111
	v_readlane_b32 s7, v255, 4
	s_load_dwordx2 s[4:5], s[4:5], 0xf0
	s_getreg_b32 s6, hwreg(HW_REG_XCC_ID, 0, 4)
	v_mov_b32_e32 v0, s7
	s_waitcnt vmcnt(0) expcnt(0) lgkmcnt(0)
	ds_read_b32 v2, v0
	v_readlane_b32 s7, v255, 5
	s_and_b32 s20, s6, 15
	s_waitcnt lgkmcnt(0)
	v_cmp_ne_u32_e32 vcc, 0, v2
	v_mov_b32_e32 v0, s7
	ds_read_b32 v0, v0
	s_cbranch_vccnz .LBB0_1011
	s_add_u32 s6, s4, 0x1000
	s_addc_u32 s7, s5, 0
	s_add_u32 s8, s4, 0x1100
	s_addc_u32 s9, s5, 0
	s_add_u32 s10, s4, 0x1200
	s_addc_u32 s11, s5, 0
	s_add_u32 s12, s4, 0x1300
	s_addc_u32 s13, s5, 0
	s_mov_b32 s21, 1
	s_branch .LBB0_999
